# attention unit start: first-tile line-touch loads issued by wave 0 only
# baseline (speedup 1.0000x reference)
.LBB0_944:
	s_bfe_u32 s0, s94, 0x40004
	s_xor_b32 s1, s0, 31
	s_cmpk_lt_i32 s94, 0x100
	s_cselect_b32 s22, s1, s0
	s_bfe_u32 s23, s94, 0x30001
	s_and_b32 s24, s94, 1
	v_readlane_b32 s32, v254, 3
	s_cmp_lg_u32 s32, 0
	s_cbranch_scc1 .Latt_touch_skip_21302
	v_readlane_b32 s0, v254, 15
	v_readlane_b32 s1, v254, 17
	s_mul_i32 s2, s23, 0x300000
	s_add_u32 s0, s0, s2
	s_addc_u32 s1, s1, 0
	s_lshl_b32 s2, s24, 7
	s_add_u32 s0, s0, s2
	s_addc_u32 s1, s1, 0
	v_mul_u32_u24_e32 v252, 0x600, v202
	v_mov_b32_e32 v253, 0
	v_lshl_add_u64 v[252:253], s[0:1], 0, v[252:253]
	global_load_dword v207, v[252:253], off offset:512
	global_load_dword v207, v[252:253], off offset:768
	s_sub_i32 s2, s22, 8
	s_max_i32 s2, s2, 0
	s_mul_i32 s2, s2, 0x18000
	v_mov_b32_e32 v250, s2
	v_mov_b32_e32 v251, 0
	v_lshl_add_u64 v[252:253], v[252:253], 0, v[250:251]
	global_load_dword v207, v[252:253], off offset:1024
	global_load_dword v207, v[252:253], off offset:1280
	v_mov_b32_e32 v250, 0x18000
	v_lshl_add_u64 v[252:253], v[252:253], 0, v[250:251]
	global_load_dword v207, v[252:253], off offset:1024
	global_load_dword v207, v[252:253], off offset:1280
.Latt_touch_skip_21302:
	s_lshl_b32 s1, s24, 14
	s_lshl_b32 s2, s23, 15
	s_or_b32 s2, s2, s1
	v_lshl_add_u64 v[6:7], v[112:113], 0, s[2:3]
	v_lshl_add_u64 v[2:3], v[6:7], 0, v[124:125]
	global_load_dwordx4 v[96:99], v[2:3], off
	v_lshl_add_u64 v[8:9], v[114:115], 0, s[2:3]
	v_lshl_add_u64 v[2:3], v[8:9], 0, v[124:125]
	global_load_dwordx4 v[100:103], v[2:3], off
	v_lshl_add_u64 v[2:3], v[6:7], 0, v[126:127]
	global_load_dwordx4 v[104:107], v[2:3], off
	v_lshl_add_u64 v[2:3], v[8:9], 0, v[126:127]
	global_load_dwordx4 v[108:111], v[2:3], off
	v_add_u32_e32 v0, v123, v134
	s_lshl_b32 s0, s24, 2
	v_lshl_or_b32 v243, s22, 6, v232
	s_add_i32 s2, s0, s96
	v_lshl_or_b32 v244, s23, 11, v243
	v_lshlrev_b32_e32 v128, 10, v244
	v_mov_b32_e32 v129, v1
	s_lshl_b32 s88, s2, 6
	s_ashr_i32 s89, s88, 31
	s_mov_b32 s0, 0xf149f2ca
	v_lshl_add_u64 v[2:3], s[82:83], 0, v[128:129]
	v_lshl_add_u64 v[2:3], s[88:89], 1, v[2:3]
	v_lshl_add_u64 v[2:3], v[116:117], 1, v[2:3]
	global_load_dwordx4 v[80:83], v[2:3], off
	global_load_dwordx4 v[84:87], v[2:3], off offset:32
	global_load_dwordx4 v[88:91], v[2:3], off offset:64
	global_load_dwordx4 v[92:95], v[2:3], off offset:96
	s_waitcnt vmcnt(7)
	ds_write_b128 v0, v[96:99] offset:21504
	s_nop 0
	v_add_u32_e32 v0, v123, v135
	s_waitcnt vmcnt(6)
	ds_write_b128 v0, v[100:103] offset:39936
	s_nop 0
	v_subrev_u32_e32 v0, 31, v243
	v_ashrrev_i32_e32 v0, 4, v0
	v_cmp_le_i32_e32 vcc, v118, v0
	s_waitcnt vmcnt(5)
	ds_write_b128 v233, v[104:107] offset:21504
	s_waitcnt vmcnt(4)
	ds_write_b128 v234, v[108:111] offset:39936
	s_waitcnt lgkmcnt(0)
	s_barrier
	ds_read_b128 v[66:69], v235 offset:21504
	ds_read_b128 v[70:73], v235 offset:21536
	ds_read_b128 v[74:77], v235 offset:21568
	ds_read_b128 v[96:99], v235 offset:21600
	ds_read_b128 v[100:103], v235 offset:26112
	ds_read_b128 v[104:107], v235 offset:26144
	s_waitcnt vmcnt(3)
	s_waitcnt lgkmcnt(5)
	v_mfma_f32_32x32x16_bf16 v[50:65], v[66:69], v[80:83], 0
	ds_read_b128 v[66:69], v235 offset:26176
	s_waitcnt vmcnt(2)
	s_waitcnt lgkmcnt(5)
	v_mfma_f32_32x32x16_bf16 v[50:65], v[70:73], v[84:87], v[50:65]
	ds_read_b128 v[70:73], v235 offset:26208
	s_waitcnt vmcnt(1)
	s_waitcnt lgkmcnt(5)
	v_mfma_f32_32x32x16_bf16 v[50:65], v[74:77], v[88:91], v[50:65]
	ds_read_b128 v[74:77], v235 offset:30720
	s_waitcnt vmcnt(0)
	s_waitcnt lgkmcnt(5)
	v_mfma_f32_32x32x16_bf16 v[50:65], v[96:99], v[92:95], v[50:65]
	ds_read_b128 v[96:99], v235 offset:30752
	s_waitcnt lgkmcnt(5)
	v_mfma_f32_32x32x16_bf16 v[34:49], v[100:103], v[80:83], 0
	ds_read_b128 v[100:103], v235 offset:30784
	s_nop 7
	v_cndmask_b32_e32 v50, v236, v50, vcc
	v_cmp_lt_i32_e32 vcc, v118, v0
	s_nop 1
	v_cndmask_b32_e32 v51, v236, v51, vcc
	v_cmp_le_i32_e32 vcc, v137, v0
	s_waitcnt lgkmcnt(5)
	v_mfma_f32_32x32x16_bf16 v[34:49], v[104:107], v[84:87], v[34:49]
	ds_read_b128 v[104:107], v235 offset:30816
	v_cndmask_b32_e32 v52, v236, v52, vcc
	v_cmp_le_i32_e32 vcc, v138, v0
	s_nop 1
	v_cndmask_b32_e32 v53, v236, v53, vcc
	v_cmp_le_i32_e32 vcc, v139, v0
	s_waitcnt lgkmcnt(5)
	v_mfma_f32_32x32x16_bf16 v[34:49], v[66:69], v[88:91], v[34:49]
	ds_read_b128 v[66:69], v235 offset:35328
	v_cndmask_b32_e32 v54, v236, v54, vcc
	v_cmp_le_i32_e32 vcc, v140, v0
	s_nop 1
	v_cndmask_b32_e32 v55, v236, v55, vcc
	v_cmp_le_i32_e32 vcc, v141, v0
	s_waitcnt lgkmcnt(5)
	v_mfma_f32_32x32x16_bf16 v[34:49], v[70:73], v[92:95], v[34:49]
	ds_read_b128 v[70:73], v235 offset:35360
	s_waitcnt lgkmcnt(5)
	v_mfma_f32_32x32x16_bf16 v[18:33], v[74:77], v[80:83], 0
	ds_read_b128 v[74:77], v235 offset:35392
	s_waitcnt lgkmcnt(5)
	v_mfma_f32_32x32x16_bf16 v[18:33], v[96:99], v[84:87], v[18:33]
	ds_read_b128 v[96:99], v235 offset:35424
	s_waitcnt lgkmcnt(5)
	v_mfma_f32_32x32x16_bf16 v[18:33], v[100:103], v[88:91], v[18:33]
	s_waitcnt lgkmcnt(4)
	v_mfma_f32_32x32x16_bf16 v[18:33], v[104:107], v[92:95], v[18:33]
	s_waitcnt lgkmcnt(3)
	v_mfma_f32_32x32x16_bf16 v[2:17], v[66:69], v[80:83], 0
	s_waitcnt lgkmcnt(2)
	v_mfma_f32_32x32x16_bf16 v[2:17], v[70:73], v[84:87], v[2:17]
	s_waitcnt lgkmcnt(1)
	v_mfma_f32_32x32x16_bf16 v[2:17], v[74:77], v[88:91], v[2:17]
	s_waitcnt lgkmcnt(0)
	v_mfma_f32_32x32x16_bf16 v[2:17], v[96:99], v[92:95], v[2:17]
	v_max3_f32 v66, v50, s0, v51
	v_max3_f32 v66, v66, v52, v53
	v_cndmask_b32_e32 v67, v236, v56, vcc
	v_cmp_le_i32_e32 vcc, v142, v0
	v_max3_f32 v66, v66, v54, v55
	s_nop 0
	v_cndmask_b32_e32 v68, v236, v57, vcc
	v_cmp_le_i32_e32 vcc, v143, v0
	v_max3_f32 v56, v66, v67, v68
	s_nop 0
	v_cndmask_b32_e32 v66, v236, v58, vcc
	v_cmp_le_i32_e32 vcc, v144, v0
	s_nop 1
	v_cndmask_b32_e32 v69, v236, v59, vcc
	v_cmp_le_i32_e32 vcc, v145, v0
	v_max3_f32 v56, v56, v66, v69
	s_nop 0
	v_cndmask_b32_e32 v70, v236, v60, vcc
	v_cmp_le_i32_e32 vcc, v146, v0
	s_nop 1
	v_cndmask_b32_e32 v71, v236, v61, vcc
	v_cmp_le_i32_e32 vcc, v147, v0
	v_max3_f32 v56, v56, v70, v71
	s_nop 0
	v_cndmask_b32_e32 v72, v236, v62, vcc
	v_cmp_le_i32_e32 vcc, v148, v0
	s_nop 1
	v_cndmask_b32_e32 v73, v236, v63, vcc
	v_cmp_le_i32_e32 vcc, v149, v0
	v_max3_f32 v56, v56, v72, v73
	s_nop 0
	v_cndmask_b32_e32 v74, v236, v64, vcc
	v_cmp_le_i32_e32 vcc, v150, v0
	s_nop 1
	v_cndmask_b32_e32 v75, v236, v65, vcc
	v_cmp_le_i32_e32 vcc, v151, v0
	v_max3_f32 v56, v56, v74, v75
	s_nop 0
	v_cndmask_b32_e32 v34, v236, v34, vcc
	v_cmp_lt_i32_e32 vcc, v151, v0
	s_nop 1
	v_cndmask_b32_e32 v35, v236, v35, vcc
	v_cmp_le_i32_e32 vcc, v152, v0
	v_max3_f32 v56, v56, v34, v35
	s_nop 0
	v_cndmask_b32_e32 v36, v236, v36, vcc
	v_cmp_le_i32_e32 vcc, v153, v0
	s_nop 1
	v_cndmask_b32_e32 v37, v236, v37, vcc
	v_cmp_le_i32_e32 vcc, v154, v0
	v_max3_f32 v56, v56, v36, v37
	s_nop 0
	v_cndmask_b32_e32 v38, v236, v38, vcc
	v_cmp_le_i32_e32 vcc, v155, v0
	s_nop 1
	v_cndmask_b32_e32 v39, v236, v39, vcc
	v_cmp_le_i32_e32 vcc, v156, v0
	v_max3_f32 v56, v56, v38, v39
	s_nop 0
	v_cndmask_b32_e32 v40, v236, v40, vcc
	v_cmp_le_i32_e32 vcc, v157, v0
	s_nop 1
	v_cndmask_b32_e32 v41, v236, v41, vcc
	v_cmp_le_i32_e32 vcc, v158, v0
	v_max3_f32 v56, v56, v40, v41
	s_nop 0
	v_cndmask_b32_e32 v42, v236, v42, vcc
	v_cmp_le_i32_e32 vcc, v159, v0
	s_nop 1
	v_cndmask_b32_e32 v43, v236, v43, vcc
	v_cmp_le_i32_e32 vcc, v160, v0
	v_max3_f32 v56, v56, v42, v43
	s_nop 0
	v_cndmask_b32_e32 v44, v236, v44, vcc
	v_cmp_le_i32_e32 vcc, v161, v0
	s_nop 1
	v_cndmask_b32_e32 v45, v236, v45, vcc
	v_cmp_le_i32_e32 vcc, v162, v0
	v_max3_f32 v56, v56, v44, v45
	s_nop 0
	v_cndmask_b32_e32 v46, v236, v46, vcc
	v_cmp_le_i32_e32 vcc, v163, v0
	s_nop 1
	v_cndmask_b32_e32 v47, v236, v47, vcc
	v_cmp_le_i32_e32 vcc, v164, v0
	v_max3_f32 v56, v56, v46, v47
	s_nop 0
	v_cndmask_b32_e32 v48, v236, v48, vcc
	v_cmp_le_i32_e32 vcc, v165, v0
	s_nop 1
	v_cndmask_b32_e32 v49, v236, v49, vcc
	v_cmp_le_i32_e32 vcc, v166, v0
	v_max3_f32 v56, v56, v48, v49
	s_nop 0
	v_cndmask_b32_e32 v76, v236, v18, vcc
	v_cmp_lt_i32_e32 vcc, v166, v0
	s_nop 1
	v_cndmask_b32_e32 v77, v236, v19, vcc
	v_cmp_le_i32_e32 vcc, v167, v0
	v_max3_f32 v18, v56, v76, v77
	s_nop 0
	v_cndmask_b32_e32 v78, v236, v20, vcc
	v_cmp_le_i32_e32 vcc, v168, v0
	s_nop 1
	v_cndmask_b32_e32 v79, v236, v21, vcc
	v_cmp_le_i32_e32 vcc, v169, v0
	v_max3_f32 v18, v18, v78, v79
	s_nop 0
	v_cndmask_b32_e32 v96, v236, v22, vcc
	v_cmp_le_i32_e32 vcc, v170, v0
	s_nop 1
	v_cndmask_b32_e32 v97, v236, v23, vcc
	v_cmp_le_i32_e32 vcc, v171, v0
	v_max3_f32 v18, v18, v96, v97
	s_nop 0
	v_cndmask_b32_e32 v98, v236, v24, vcc
	v_cmp_le_i32_e32 vcc, v172, v0
	s_nop 1
	v_cndmask_b32_e32 v99, v236, v25, vcc
	v_cmp_le_i32_e32 vcc, v173, v0
	v_max3_f32 v18, v18, v98, v99
	s_nop 0
	v_cndmask_b32_e32 v100, v236, v26, vcc
	v_cmp_le_i32_e32 vcc, v174, v0
	s_nop 1
	v_cndmask_b32_e32 v101, v236, v27, vcc
	v_cmp_le_i32_e32 vcc, v175, v0
	v_max3_f32 v18, v18, v100, v101
	s_nop 0
	v_cndmask_b32_e32 v102, v236, v28, vcc
	v_cmp_le_i32_e32 vcc, v176, v0
	s_nop 1
	v_cndmask_b32_e32 v103, v236, v29, vcc
	v_cmp_le_i32_e32 vcc, v177, v0
	v_max3_f32 v18, v18, v102, v103
	s_nop 0
	v_cndmask_b32_e32 v104, v236, v30, vcc
	v_cmp_le_i32_e32 vcc, v178, v0
	s_nop 1
	v_cndmask_b32_e32 v105, v236, v31, vcc
	v_cmp_le_i32_e32 vcc, v179, v0
	v_max3_f32 v18, v18, v104, v105
	s_nop 0
	v_cndmask_b32_e32 v106, v236, v32, vcc
	v_cmp_le_i32_e32 vcc, v180, v0
	s_nop 1
	v_cndmask_b32_e32 v107, v236, v33, vcc
	v_cmp_le_i32_e32 vcc, v181, v0
	v_max3_f32 v18, v18, v106, v107
	s_nop 0
	v_cndmask_b32_e32 v108, v236, v2, vcc
	v_cmp_lt_i32_e32 vcc, v181, v0
	s_nop 1
	v_cndmask_b32_e32 v109, v236, v3, vcc
	v_cmp_le_i32_e32 vcc, v182, v0
	v_max3_f32 v2, v18, v108, v109
	s_nop 0
	v_cndmask_b32_e32 v110, v236, v4, vcc
	v_cmp_le_i32_e32 vcc, v183, v0
	s_nop 1
	v_cndmask_b32_e32 v111, v236, v5, vcc
	v_cmp_le_i32_e32 vcc, v184, v0
	v_max3_f32 v2, v2, v110, v111
	s_nop 0
	v_cndmask_b32_e32 v129, v236, v6, vcc
	v_cmp_le_i32_e32 vcc, v185, v0
	s_nop 1
	v_cndmask_b32_e32 v130, v236, v7, vcc
	v_cmp_le_i32_e32 vcc, v186, v0
	v_max3_f32 v2, v2, v129, v130
	s_nop 0
	v_cndmask_b32_e32 v56, v236, v8, vcc
	v_cmp_le_i32_e32 vcc, v187, v0
	s_nop 1
	v_cndmask_b32_e32 v57, v236, v9, vcc
	v_cmp_le_i32_e32 vcc, v188, v0
	v_max3_f32 v2, v2, v56, v57
	s_nop 0
	v_cndmask_b32_e32 v58, v236, v10, vcc
	v_cmp_le_i32_e32 vcc, v189, v0
	s_nop 1
	v_cndmask_b32_e32 v59, v236, v11, vcc
	v_cmp_le_i32_e32 vcc, v190, v0
	v_max3_f32 v2, v2, v58, v59
	s_nop 0
	v_cndmask_b32_e32 v62, v236, v12, vcc
	v_cmp_le_i32_e32 vcc, v191, v0
	s_nop 1
	v_cndmask_b32_e32 v63, v236, v13, vcc
	v_cmp_le_i32_e32 vcc, v192, v0
	v_max3_f32 v2, v2, v62, v63
	s_nop 0
	v_cndmask_b32_e32 v65, v236, v14, vcc
	v_cmp_le_i32_e32 vcc, v193, v0
	s_nop 1
	v_cndmask_b32_e32 v64, v236, v15, vcc
	v_cmp_le_i32_e32 vcc, v194, v0
	v_max3_f32 v2, v2, v65, v64
	s_nop 0
	v_cndmask_b32_e32 v61, v236, v16, vcc
	v_cmp_le_i32_e32 vcc, v195, v0
	s_nop 1
	v_cndmask_b32_e32 v0, v236, v17, vcc
	v_max3_f32 v2, v2, v61, v0
	ds_bpermute_b32 v3, v196, v2
	v_cmp_lt_u32_e32 vcc, 30, v243
	s_waitcnt lgkmcnt(0)
	v_max_f32_e32 v3, v3, v3
	v_max_f32_e32 v60, v2, v3
	v_sub_f32_e32 v2, v50, v60
	v_exp_f32_e32 v2, v2
	v_sub_f32_e32 v3, v51, v60
	v_exp_f32_e32 v3, v3
	v_sub_f32_e32 v13, v70, v60
	v_add_f32_e32 v4, 0, v2
	v_exp_f32_e32 v14, v13
	v_add_f32_e32 v5, v3, v4
	v_sub_f32_e32 v4, v52, v60
	v_exp_f32_e32 v4, v4
	v_sub_f32_e32 v13, v71, v60
	v_exp_f32_e32 v15, v13
	v_sub_f32_e32 v13, v72, v60
	v_add_f32_e32 v6, v4, v5
	v_sub_f32_e32 v5, v53, v60
	v_exp_f32_e32 v5, v5
	v_exp_f32_e32 v18, v13
	v_sub_f32_e32 v13, v73, v60
	v_exp_f32_e32 v19, v13
	v_add_f32_e32 v7, v5, v6
	v_sub_f32_e32 v6, v54, v60
	v_exp_f32_e32 v6, v6
	v_sub_f32_e32 v13, v74, v60
	v_exp_f32_e32 v20, v13
	v_sub_f32_e32 v13, v75, v60
	v_add_f32_e32 v8, v6, v7
	v_sub_f32_e32 v7, v55, v60
	v_exp_f32_e32 v7, v7
	v_exp_f32_e32 v21, v13
	v_sub_f32_e32 v29, v44, v60
	v_exp_f32_e32 v30, v29
	v_add_f32_e32 v9, v7, v8
	v_sub_f32_e32 v8, v67, v60
	v_exp_f32_e32 v8, v8
	v_sub_f32_e32 v29, v45, v60
	v_exp_f32_e32 v31, v29
	v_sub_f32_e32 v29, v46, v60
	v_add_f32_e32 v10, v8, v9
	v_sub_f32_e32 v9, v68, v60
	v_exp_f32_e32 v9, v9
	v_sub_f32_e32 v45, v102, v60
	v_exp_f32_e32 v46, v45
	v_sub_f32_e32 v45, v103, v60
	v_add_f32_e32 v11, v9, v10
	v_sub_f32_e32 v10, v66, v60
	v_exp_f32_e32 v10, v10
	v_sub_f32_e32 v56, v56, v60
	v_exp_f32_e32 v56, v56
	v_sub_f32_e32 v57, v57, v60
	v_add_f32_e32 v12, v10, v11
	v_sub_f32_e32 v11, v69, v60
	v_exp_f32_e32 v11, v11
	v_exp_f32_e32 v57, v57
	v_sub_f32_e32 v58, v58, v60
	v_exp_f32_e32 v58, v58
	v_add_f32_e32 v12, v11, v12
	v_add_f32_e32 v12, v14, v12
	v_add_f32_e32 v12, v15, v12
	v_add_f32_e32 v12, v18, v12
	v_add_f32_e32 v12, v19, v12
	v_add_f32_e32 v12, v20, v12
	v_add_f32_e32 v13, v21, v12
	v_sub_f32_e32 v12, v34, v60
	v_exp_f32_e32 v12, v12
	v_exp_f32_e32 v34, v29
	v_sub_f32_e32 v29, v47, v60
	v_exp_f32_e32 v47, v45
	v_add_f32_e32 v16, v12, v13
	v_sub_f32_e32 v13, v35, v60
	v_exp_f32_e32 v13, v13
	v_exp_f32_e32 v35, v29
	v_sub_f32_e32 v29, v48, v60
	v_sub_f32_e32 v45, v104, v60
	v_add_f32_e32 v17, v13, v16
	v_sub_f32_e32 v16, v36, v60
	v_exp_f32_e32 v16, v16
	v_exp_f32_e32 v36, v29
	v_sub_f32_e32 v29, v49, v60
	v_exp_f32_e32 v50, v45
	v_add_f32_e32 v22, v16, v17
	v_sub_f32_e32 v17, v37, v60
	v_exp_f32_e32 v17, v17
	v_exp_f32_e32 v37, v29
	v_sub_f32_e32 v45, v105, v60
	v_exp_f32_e32 v51, v45
	v_add_f32_e32 v23, v17, v22
	v_sub_f32_e32 v22, v38, v60
	v_exp_f32_e32 v22, v22
	v_sub_f32_e32 v45, v106, v60
	v_exp_f32_e32 v52, v45
	v_sub_f32_e32 v45, v107, v60
	v_add_f32_e32 v24, v22, v23
	v_sub_f32_e32 v23, v39, v60
	v_exp_f32_e32 v23, v23
	v_exp_f32_e32 v53, v45
	v_sub_f32_e32 v59, v59, v60
	v_exp_f32_e32 v59, v59
	v_add_f32_e32 v25, v23, v24
	v_sub_f32_e32 v24, v40, v60
	v_exp_f32_e32 v24, v24
	v_sub_f32_e32 v62, v62, v60
	v_exp_f32_e32 v62, v62
	v_sub_f32_e32 v63, v63, v60
	v_add_f32_e32 v26, v24, v25
	v_sub_f32_e32 v25, v41, v60
	v_exp_f32_e32 v25, v25
	v_exp_f32_e32 v63, v63
	v_sub_f32_e32 v65, v65, v60
	v_sub_f32_e32 v64, v64, v60
	v_add_f32_e32 v27, v25, v26
	v_sub_f32_e32 v26, v42, v60
	v_exp_f32_e32 v26, v26
	v_sub_f32_e32 v61, v61, v60
	v_sub_f32_e32 v0, v0, v60
	v_add_f32_e32 v28, v26, v27
	v_sub_f32_e32 v27, v43, v60
	v_exp_f32_e32 v27, v27
	s_nop 0
	v_add_f32_e32 v28, v27, v28
	v_add_f32_e32 v28, v30, v28
	v_add_f32_e32 v28, v31, v28
	v_add_f32_e32 v28, v34, v28
	v_add_f32_e32 v28, v35, v28
	v_add_f32_e32 v28, v36, v28
	v_add_f32_e32 v29, v37, v28
	v_sub_f32_e32 v28, v76, v60
	v_exp_f32_e32 v28, v28
	v_exp_f32_e32 v76, v65
	v_add_f32_e32 v32, v28, v29
	v_sub_f32_e32 v29, v77, v60
	v_exp_f32_e32 v29, v29
	v_exp_f32_e32 v77, v64
	v_add_f32_e32 v33, v29, v32
	v_sub_f32_e32 v32, v78, v60
	v_exp_f32_e32 v32, v32
	v_exp_f32_e32 v78, v61
	v_add_f32_e32 v38, v32, v33
	v_sub_f32_e32 v33, v79, v60
	v_exp_f32_e32 v33, v33
	v_exp_f32_e32 v79, v0
	v_mov_b32_e32 v0, v1
	v_add_f32_e32 v39, v33, v38
	v_sub_f32_e32 v38, v96, v60
	v_exp_f32_e32 v38, v38
	s_nop 0
	v_add_f32_e32 v40, v38, v39
	v_sub_f32_e32 v39, v97, v60
	v_exp_f32_e32 v39, v39
	s_nop 0
	v_add_f32_e32 v41, v39, v40
	v_sub_f32_e32 v40, v98, v60
	v_exp_f32_e32 v40, v40
	s_nop 0
	v_add_f32_e32 v42, v40, v41
	v_sub_f32_e32 v41, v99, v60
	v_exp_f32_e32 v41, v41
	s_nop 0
	v_add_f32_e32 v43, v41, v42
	v_sub_f32_e32 v42, v100, v60
	v_exp_f32_e32 v42, v42
	s_nop 0
	v_add_f32_e32 v44, v42, v43
	v_sub_f32_e32 v43, v101, v60
	v_exp_f32_e32 v43, v43
	s_nop 0
	v_add_f32_e32 v44, v43, v44
	v_add_f32_e32 v44, v46, v44
	v_add_f32_e32 v44, v47, v44
	v_add_f32_e32 v44, v50, v44
	v_add_f32_e32 v44, v51, v44
	v_add_f32_e32 v44, v52, v44
	v_add_f32_e32 v45, v53, v44
	v_sub_f32_e32 v44, v108, v60
	v_exp_f32_e32 v44, v44
	s_nop 0
	v_add_f32_e32 v48, v44, v45
	v_sub_f32_e32 v45, v109, v60
	v_exp_f32_e32 v45, v45
	s_nop 0
	v_add_f32_e32 v49, v45, v48
	v_sub_f32_e32 v48, v110, v60
	v_exp_f32_e32 v48, v48
	s_nop 0
	v_add_f32_e32 v54, v48, v49
	v_sub_f32_e32 v49, v111, v60
	v_exp_f32_e32 v49, v49
	s_nop 0
	v_add_f32_e32 v55, v49, v54
	v_sub_f32_e32 v54, v129, v60
	v_exp_f32_e32 v54, v54
	s_nop 0
	v_add_f32_e32 v66, v54, v55
	v_sub_f32_e32 v55, v130, v60
	v_exp_f32_e32 v55, v55
	s_nop 0
	v_add_f32_e32 v66, v55, v66
	v_add_f32_e32 v66, v56, v66
	v_add_f32_e32 v66, v57, v66
	v_add_f32_e32 v66, v58, v66
	v_add_f32_e32 v66, v59, v66
	v_add_f32_e32 v66, v62, v66
	v_add_f32_e32 v66, v63, v66
	v_add_f32_e32 v65, v76, v66
	v_add_f32_e32 v64, v77, v65
	v_add_f32_e32 v61, v78, v64
	v_add_f32_e32 v60, v79, v61
	ds_bpermute_b32 v61, v196, v60
	s_and_saveexec_b64 s[0:1], vcc
	s_cbranch_execz .LBB0_946
	s_waitcnt lgkmcnt(0)
	v_add_f32_e32 v0, v60, v61
	v_div_scale_f32 v60, s[26:27], v0, v0, 1.0
	v_rcp_f32_e32 v61, v60
	v_div_scale_f32 v64, vcc, 1.0, v0, 1.0
	v_fma_f32 v65, -v60, v61, 1.0
	v_fmac_f32_e32 v61, v65, v61
	v_mul_f32_e32 v65, v64, v61
	v_fma_f32 v66, -v60, v65, v64
	v_fmac_f32_e32 v65, v66, v61
	v_fma_f32 v60, -v60, v65, v64
	v_div_fmas_f32 v60, v60, v61, v65
	v_div_fixup_f32 v0, v60, v0, 1.0
